# mixer unit queue: next unit index fetched during the current unit's last tile/segment/chunk (hides the dequeue round trip)
# speedup vs baseline: 1.0041x; 1.0041x over previous
; __global__ void __launch_bounds__(512, 2) mega_fwd(Args a) {
;     ...
;     for (int ph = ph_lo; ph < ph_hi; ++ph) {
;     ArgP ap = (ArgP)__builtin_amdgcn_kernarg_segment_ptr(); asm volatile("" : "+s"(ap));
;     int tid = threadIdx.x; asm volatile("" : "+v"(tid));
;     int bid = blockIdx.x; asm volatile("" : "+s"(bid));
;     int nbk = gridDim.x; asm volatile("" : "+s"(nbk));
;     unsigned char* ws = ap->ws;
;     unsigned char* wb = ws + WS_W;
;     bf16_t* xn = (bf16_t*)(ws + WS_XN);
;     bf16_t* act = (bf16_t*)(ws + WS_BIG);
;     bf16_t *zA = (bf16_t*)(ws + WS_ZA), *zB = (bf16_t*)(ws + WS_ZB), *zC = (bf16_t*)(ws + WS_ZC), *zG = (bf16_t*)(ws + WS_ZG);
;     float* mF = (float*)(ws + WS_MF); bf16_t* mB = (bf16_t*)(ws + WS_MB);
;     bf16_t *ya = (bf16_t*)(ws + WS_YA), *yb = ya + 512, *yc = ya + 1024, *OP = (bf16_t*)(ws + WS_OP);
;     float* LSE = (float*)(ws + WS_LSE);
;     unsigned* RS = (unsigned*)(ws + WS_RS);
;     const float* x = ap->in[0]; float* out = ap->out;
;         if (ph == NPH - 1) {
.LBB0_11:
	s_mov_b32 s98, 0
	v_readlane_b32 s12, v254, 2
	s_mov_b64 s[0:1], s[92:93]
	v_mov_b32_e32 v187, v174
	s_mov_b32 s11, s2
	s_mov_b32 s10, s12
	s_load_dwordx2 s[60:61], s[0:1], 0xc0
	v_readlane_b32 s13, v254, 3
	s_mov_b64 s[44:45], 0
	s_mov_b64 s[12:13], -1
	s_waitcnt lgkmcnt(0)
	s_add_u32 s38, s60, 0x3800000
	s_addc_u32 s39, s61, 0
	s_cmp_lg_u32 s7, 34
	s_cbranch_scc1 .LBB0_14
	s_and_b64 vcc, exec, s[12:13]
	s_cbranch_vccnz .LBB0_545

; __global__ void __launch_bounds__(512, 2) mega_fwd(Args a) {
;     ...
;                     for (;;) {
;                         __syncthreads();
;                         if (tid == 0) *shu = (int)atomicAdd(counter, 1u);
;                         __syncthreads();
.Lpf_hg:
	s_and_saveexec_b64 s[100:101], s[40:41]
	s_cbranch_execz .Lpf_skip_hg
	v_mov_b32_e32 v185, 1
	global_atomic_add v253, v2, v185, s[68:69] sc0
.Lpf_skip_hg:
	s_or_b64 exec, exec, s[100:101]
	s_mov_b32 s98, 1
	s_branch .LBB0_193
.Lpf_dl:
	s_and_saveexec_b64 s[100:101], s[40:41]
	s_cbranch_execz .Lpf_skip_dl
	v_mov_b32_e32 v185, 1
	global_atomic_add v253, v2, v185, s[76:77] sc0

; __global__ void __launch_bounds__(512, 2) mega_fwd(Args a) {
;     ...
;                     for (;;) {
;                         __syncthreads();
;                         if (tid == 0) *shu = (int)atomicAdd(counter, 1u);
;                         __syncthreads();
.LBB0_162:
	s_barrier
	s_and_saveexec_b64 s[42:43], s[40:41]
	s_cbranch_execz .LBB0_166
	s_mov_b64 s[46:47], exec
	v_mbcnt_lo_u32_b32 v0, s46, 0
	v_mbcnt_hi_u32_b32 v0, s47, v0
	v_cmp_eq_u32_e32 vcc, 0, v0
	s_and_saveexec_b64 s[44:45], vcc
	s_cbranch_execz .LBB0_165
	s_cmp_eq_u32 s98, 1
	s_cbranch_scc0 .Lq_fetch
	s_waitcnt vmcnt(0)
	v_mov_b32_e32 v1, v253
	s_branch .Lq_have

; __device__ __forceinline__ void dil_unit(LAS unsigned char* lds, const bf16_t* zB, bf16_t* OP, float* LSE, int bl, int h, int pi, int su, float slope, int tid) {
;     const int lane = tid & 63, wv = __builtin_amdgcn_readfirstlane(tid >> 6), fr = lane & 15, quad = lane >> 4;
; __global__ void __launch_bounds__(512, 2) mega_fwd(Args a) {
;     ...
;                         if (tid == 0) *shu = (int)atomicAdd(counter, 1u);
;                         __syncthreads();
;                         const int u = *shu;
;                         if (u >= NU_ALL + PROBE_DUP_H * NU_H + PROBE_DUP_A * (NU_D + NU_L)) break;
;                         int tidu = tid; asm volatile("" : "+v"(tidu));
;                         int u2 = u;
;     ...
;                         const bool dummy = u2 < NU_H; if (!dummy) u2 -= NU_H;
;     ...
;                         const bool dummy = false;
;     ...
;                         if (u2 >= NU_ALL) u2 -= (NU_D + NU_L);
;     ...
;                         if (dummy || u2 < NU_H) {
;                             const int dir = u2 & 1, h = (u2 >> 1) & 3, bl = u2 >> 3;
;                             float lb = 0.f;
;                             if (l == 1) { const int k = tidu & 127; const float x0 = ap->in[12][h * 128 + k], x1 = ap->in[12][512 + h * 128 + k]; const float mx = fmaxf(x0, x1); const float e0 = expf(x0 - mx), e1 = expf(x1 - mx); lb = e1 / (e0 + e1); }
;                             if (dummy) hgrn_unit(lds, zC, bl, h, dir, lb, tidu, OP, 1024, dir * 512 + h * 128);
;                             else hgrn_unit(lds, zC, bl, h, dir, lb, tidu, zC, 2560, 512 + dir * 512 + h * 128);
;                         } else if (u2 < NU_H + NU_D) {
;                             const int v = u2 - NU_H, qt = v & 15, h = (v >> 4) & 3, bl = v >> 6;
;                             const float slope = exp2f(-8.0f * (float)(3 * h + 1) / 12.0f);
;                             diff_unit(lds, zA, ya, bl, h, qt, slope, lam, 1.f - lam_init, ap->in[11] + l * 128, tidu);
;                         } else {
;                             const int v = u2 - NU_H - NU_D, s16 = v & 3, t = v >> 2, pi = t % 3, t2 = t / 3, h = t2 & 7, bl = t2 >> 3;
;                             const int aidx = h + 1 + (h >> 1);
;                             const float slope = exp2f(-8.0f * (float)(aidx + 1) / 12.0f);
;                             dil_unit(lds, zB, OP, LSE, bl, h, pi, s16, slope, tidu);
.Lq_have:
.LBB0_165:
	s_or_b64 exec, exec, s[44:45]
	s_waitcnt vmcnt(0)
	v_readfirstlane_b32 s14, v1
	s_nop 1
	v_add_u32_e32 v0, s14, v0
	v_readlane_b32 s14, v255, 17
	s_nop 1
	v_mov_b32_e32 v1, s14
	ds_write_b32 v1, v0
.LBB0_166:
	s_or_b64 exec, exec, s[42:43]
	s_mov_b32 s98, 0
	v_readlane_b32 s14, v255, 17
	s_waitcnt lgkmcnt(0)
	s_barrier
	v_mov_b32_e32 v0, s14
	ds_read_b32 v0, v0
	s_movk_i32 s14, 0x53f
	s_mov_b64 s[42:43], -1
	s_waitcnt lgkmcnt(0)
	v_cmp_lt_i32_e32 vcc, s14, v0
	v_readfirstlane_b32 s74, v0
	s_cbranch_vccnz .LBB0_161
	v_mov_b32_e32 v152, v187
	s_cmp_gt_i32 s74, 63
	s_cbranch_scc0 .LBB0_187
	s_cmpk_gt_u32 s74, 0x23f
	s_cbranch_scc0 .LBB0_182
	s_add_i32 s14, s74, 0xfffffdc0
	s_mul_i32 s30, s14, 0xaaab
	s_lshr_b32 s42, s30, 19
	s_lshr_b32 s15, s14, 2
	s_bfe_u32 s14, s30, 0x30013
	s_bfe_u32 s42, s42, 0x20001
	s_add_i32 s42, s42, s14
	s_lshl_b32 s42, s42, 3
	s_sub_i32 s42, -16, s42
	v_cvt_f32_i32_e32 v0, s42
	s_mul_i32 s42, s15, 0xab
	s_mov_b32 s2, 0x41400000
	s_bfe_u32 s44, s42, 0x70009
	v_div_scale_f32 v1, s[42:43], s2, s2, v0
	v_rcp_f32_e32 v3, v1
	s_mul_i32 s44, s44, 3
	s_sub_i32 s15, s15, s44
	s_and_b32 s46, s15, 0xff
	v_fma_f32 v4, -v1, v3, 1.0
	v_fmac_f32_e32 v3, v4, v3
	v_div_scale_f32 v4, vcc, v0, s2, v0
	v_mul_f32_e32 v5, v4, v3
	v_fma_f32 v6, -v1, v5, v4
	v_fmac_f32_e32 v5, v6, v3
	v_fma_f32 v1, -v1, v5, v4
	v_div_fmas_f32 v1, v1, v3, v5
	v_div_fixup_f32 v38, v1, s2, v0
	s_mov_b32 s2, 0xc2fc0000
	v_cmp_gt_f32_e32 vcc, s2, v38
	s_and_b64 s[42:43], vcc, exec
	v_mov_b32_e32 v0, 0x42800000
	s_cselect_b32 s15, 0xffffffc0, 0
	s_cmp_eq_u32 s46, 1
	v_cndmask_b32_e32 v39, 0, v0, vcc
	s_cselect_b64 s[42:43], -1, 0
	v_mov_b32_e32 v0, 0x41800000
	v_cndmask_b32_e64 v0, v0, 4.0, s[42:43]
	s_and_b64 s[42:43], s[42:43], exec
	s_cselect_b32 s44, 2, 4
	s_cmp_eq_u32 s46, 0
	s_cselect_b64 s[42:43], -1, 0
	v_cndmask_b32_e64 v44, v0, 1.0, s[42:43]
	s_and_b64 s[42:43], s[42:43], exec
	s_cselect_b32 s62, 0, s44
	s_lshr_b32 s85, 16, s62
	s_lshl_b32 s42, s74, 2
	s_and_b32 s75, s42, 12
	s_add_i32 s85, s85, -1
	s_and_b32 s42, s85, s75
	s_lshr_b32 s63, 0x800, s62
	s_lshr_b32 s30, s30, 11
	s_sub_i32 s84, 4, s62
	s_lshl_b32 s50, s42, 7
	s_and_b32 s30, s30, 0x1ff800
	s_lshr_b32 s47, s75, s84
	s_sub_i32 s43, s50, 64
	s_add_i32 s86, s63, -1
	s_lshl_b32 s42, s14, 7
	s_add_u32 s44, s78, s42
	v_lshlrev_b32_e32 v0, 4, v152
	v_ashrrev_i32_e32 v3, 3, v152
	s_waitcnt vmcnt(8)
	v_add_u32_e32 v12, 0x200, v152
	s_addc_u32 s45, s79, 0
	v_and_b32_e32 v36, 0x70, v0
	v_mov_b32_e32 v37, v2
	v_add_u32_e32 v4, s43, v3
	v_ashrrev_i32_e32 v120, 3, v12
	s_waitcnt vmcnt(6)
	v_add_u32_e32 v20, 0x400, v152
	v_lshl_add_u64 v[0:1], s[44:45], 0, v[36:37]
	v_min_i32_e32 v5, s86, v4
	v_cmp_lt_i32_e32 vcc, -1, v4
	v_add_u32_e32 v12, s43, v120
	v_ashrrev_i32_e32 v121, 3, v20
	s_waitcnt vmcnt(4)
	v_add_u32_e32 v28, 0x600, v152
	v_add_f32_e32 v37, v38, v39
	v_cndmask_b32_e32 v4, 0, v5, vcc
	v_min_i32_e32 v13, s86, v12
	v_cmp_lt_i32_e32 vcc, -1, v12
	v_add_u32_e32 v20, s43, v121
	v_ashrrev_i32_e32 v122, 3, v28
	v_exp_f32_e32 v37, v37
	v_cndmask_b32_e32 v12, 0, v13, vcc
	v_min_i32_e32 v21, s86, v20
	v_cmp_lt_i32_e32 vcc, -1, v20
	v_add_u32_e32 v28, s43, v122
	v_min_i32_e32 v29, s86, v28
	v_cndmask_b32_e32 v20, 0, v21, vcc
	v_cmp_lt_i32_e32 vcc, -1, v28
	v_lshlrev_b32_e32 v4, s62, v4
	s_or_b32 s51, s30, s47
	v_cndmask_b32_e32 v28, 0, v29, vcc
	v_lshlrev_b32_e32 v12, s62, v12
	v_lshlrev_b32_e32 v20, s62, v20
	v_lshlrev_b32_e32 v28, s62, v28
	v_ldexp_f32 v37, v37, s15
	v_readfirstlane_b32 s15, v152
	v_add_u32_e32 v4, s51, v4
	v_add_u32_e32 v12, s51, v12
	v_add_u32_e32 v20, s51, v20
	v_add_u32_e32 v28, s51, v28
	s_ashr_i32 s15, s15, 2
	v_mad_u64_u32 v[8:9], s[48:49], v4, s9, v[0:1]
	v_mad_u64_u32 v[16:17], s[48:49], v12, s9, v[0:1]
	v_mad_u64_u32 v[24:25], s[48:49], v20, s9, v[0:1]
	v_mad_u64_u32 v[32:33], s[48:49], v28, s9, v[0:1]
	s_and_b32 s51, s15, -16
	v_and_b32_e32 v45, 15, v152
	s_add_i32 s48, s51, s50
	v_or_b32_e32 v38, s48, v45
	v_lshlrev_b32_e32 v38, s62, v38
	v_add_u32_e32 v38, s47, v38
	v_ashrrev_i32_e32 v39, 31, v38
	v_lshl_add_u64 v[38:39], v[38:39], 0, s[30:31]
	v_mov_b64_e32 v[40:41], s[78:79]
	v_mad_u64_u32 v[40:41], s[48:49], v38, s9, v[40:41]
	s_mov_b32 s43, s31
	v_bfe_u32 v46, v152, 4, 2
	v_mad_i32_i24 v41, v39, s9, v41
	v_lshl_add_u64 v[38:39], v[40:41], 0, s[42:43]
	v_lshlrev_b32_e32 v42, 4, v46
	v_mov_b32_e32 v43, v2
	v_lshl_add_u64 v[38:39], v[38:39], 0, v[42:43]
	global_load_dwordx4 v[4:7], v[8:9], off offset:1024
	s_nop 0
	global_load_dwordx4 v[8:11], v[8:9], off offset:2048
	s_nop 0
	global_load_dwordx4 v[12:15], v[16:17], off offset:1024
	s_nop 0
	global_load_dwordx4 v[16:19], v[16:17], off offset:2048
	s_nop 0
	global_load_dwordx4 v[20:23], v[24:25], off offset:1024
	s_nop 0
	global_load_dwordx4 v[24:27], v[24:25], off offset:2048
	s_nop 0
	global_load_dwordx4 v[28:31], v[32:33], off offset:1024
	s_nop 0
	global_load_dwordx4 v[32:35], v[32:33], off offset:2048
	s_nop 0
	global_load_dwordx4 v[80:83], v[38:39], off
	global_load_dwordx4 v[84:87], v[38:39], off offset:64
	s_movk_i32 s2, 0xa0
	v_add_u32_e32 v36, 0, v36
	v_mul_lo_u32 v38, v3, s2
	v_add_u32_e32 v123, v36, v38
	v_mul_lo_u32 v38, v120, s2
	v_add_u32_e32 v124, v36, v38
	v_mul_lo_u32 v38, v121, s2
	v_add_u32_e32 v125, v36, v38
	v_mul_lo_u32 v38, v122, s2
	v_add_u32_e32 v126, v36, v38
	v_or_b32_e32 v36, 64, v45
	v_lshlrev_b32_e32 v128, 2, v46
	v_sub_u32_e32 v79, v36, v128
	v_subrev_u32_e32 v48, 50, v79
	v_subrev_u32_e32 v50, 51, v79
	v_subrev_u32_e32 v52, 48, v79
	v_cvt_f32_u32_e32 v51, v50
	v_cvt_f32_u32_e32 v50, v48
	v_cvt_f32_u32_e32 v48, v52
	v_add_u32_e32 v52, 0xffffffbf, v79
; #define DL_STORE() do { _Pragma("unroll") for (int j = 0; j < 4; ++j) { const int id = tid + j * 512, row = id >> 3, ch = id & 7; \
;             *(LAS u32x4*)(lds + row * DL_STR + ch * 16) = kv_[j]; *(LAS u32x4*)(lds + DL_KB + row * DL_STR + ch * 16) = vv_[j]; } } while (0)
; template <int DVT, int NKB, bool MASKED, bool EDGE = true> ...
;     ...
;             f32x4 acc = {0.f, 0.f, 0.f, 0.f};
;             if (DEAD) { acc = (f32x4){-1e30f, -1e30f, -1e30f, -1e30f}; }
;             else {
; #pragma unroll
;                 for (int j = 0; j < 4; ++j) acc[j] = nslope * __builtin_fabsf(relq - (float)(nb * 32 + t * 16 + j));
; __device__ __forceinline__ void dil_unit(LAS unsigned char* lds, const bf16_t* zB, bf16_t* OP, float* LSE, int bl, int h, int pi, int su, float slope, int tid) {
;     ...
;     DL_LOAD(4 * su);
;     DL_STORE();
;     __syncthreads();
	v_subrev_u32_e32 v53, 64, v79
	v_add_u32_e32 v54, 0xffffffbd, v79
	v_add_u32_e32 v55, 0xffffffbe, v79
	v_cvt_f32_i32_e32 v52, v52
	v_cvt_f32_i32_e32 v56, v53
	v_cvt_f32_i32_e32 v54, v54
	v_cvt_f32_i32_e32 v57, v55
	v_and_b32_e32 v53, 0x7fffffff, v52
	v_and_b32_e32 v52, 0x7fffffff, v56
	v_and_b32_e32 v55, 0x7fffffff, v54
	v_and_b32_e32 v54, 0x7fffffff, v57
	v_add_u32_e32 v56, 0xffffffaf, v79
	v_add_u32_e32 v57, 0xffffffb0, v79
	v_add_u32_e32 v58, 0xffffffad, v79
	v_add_u32_e32 v59, 0xffffffae, v79
	v_cvt_f32_i32_e32 v56, v56
	v_cvt_f32_i32_e32 v60, v57
	v_cvt_f32_i32_e32 v58, v58
	v_cvt_f32_i32_e32 v61, v59
	v_xor_b32_e32 v57, 0x80000000, v56
	v_xor_b32_e32 v56, 0x80000000, v60
	v_xor_b32_e32 v59, 0x80000000, v58
	v_xor_b32_e32 v58, 0x80000000, v61
	v_add_u32_e32 v60, 0xffffff9f, v79
	v_add_u32_e32 v61, 0xffffffa0, v79
	v_add_u32_e32 v62, 0xffffff9d, v79
	v_add_u32_e32 v63, 0xffffff9e, v79
	v_cvt_f32_i32_e32 v60, v60
	v_cvt_f32_i32_e32 v64, v61
	v_cvt_f32_i32_e32 v62, v62
	v_cvt_f32_i32_e32 v65, v63
	v_xor_b32_e32 v61, 0x80000000, v60
	v_xor_b32_e32 v60, 0x80000000, v64
	v_xor_b32_e32 v63, 0x80000000, v62
	v_xor_b32_e32 v62, 0x80000000, v65
	v_add_u32_e32 v64, 0xffffff8f, v79
	v_add_u32_e32 v65, 0xffffff90, v79
	v_add_u32_e32 v66, 0xffffff8d, v79
	v_add_u32_e32 v67, 0xffffff8e, v79
	v_cvt_f32_i32_e32 v64, v64
	v_cvt_f32_i32_e32 v68, v65
	v_cvt_f32_i32_e32 v66, v66
	v_cvt_f32_i32_e32 v69, v67
	s_lshl_b32 s43, s46, 14
	s_mov_b64 s[82:83], s[72:73]
	s_mov_b64 s[72:73], s[64:65]
	v_bfi_b32 v127, -16, s15, v152
	s_sub_i32 s64, s51, 64
	s_add_i32 s15, s63, 0xffffff60
	s_add_i32 s88, s43, s30
	v_readlane_b32 s2, v255, 42
	v_xor_b32_e32 v65, 0x80000000, v64
	v_xor_b32_e32 v64, 0x80000000, v68
	v_or_b32_e32 v68, 0xffffff80, v79
	s_add_u32 s42, s2, s42
	v_readlane_b32 s2, v255, 43
	s_mulk_i32 s51, 0xa0
	v_xor_b32_e32 v67, 0x80000000, v66
	v_xor_b32_e32 v66, 0x80000000, v69
	v_cvt_f32_i32_e32 v90, v68
	v_add_u32_e32 v68, 0xffffff7f, v79
	v_add_u32_e32 v69, 0xffffff7e, v79
	v_lshlrev_b32_e32 v40, 3, v46
	v_mov_b32_e32 v41, v2
	s_addc_u32 s43, s2, 0
	s_add_i32 s65, s51, 0
	v_mul_f32_e32 v37, 0xbfb8aa3b, v37
	v_cvt_f32_i32_e32 v73, v69
	v_cvt_f32_i32_e32 v72, v68
	v_lshl_add_u64 v[116:117], s[44:45], 0, v[42:43]
	v_lshl_add_u64 v[118:119], s[42:43], 0, v[40:41]
	v_mul_f32_e32 v70, v44, v37
	v_add_u32_e32 v77, s65, v42
	v_subrev_u32_e32 v40, 18, v79
	v_subrev_u32_e32 v42, 19, v79
	v_add_u32_e32 v44, -16, v79
	v_add_u32_e32 v68, 0xffffff7d, v79
	v_cmp_eq_u32_e64 s[42:43], 0, v46
	v_mul_u32_u24_e32 v78, 0xa0, v45
	v_add_u32_e32 v37, -1, v79
	v_add_u32_e32 v88, -2, v79
	v_add_u32_e32 v89, -3, v79
	v_subrev_u32_e32 v41, 17, v79
	v_cvt_f32_u32_e32 v43, v42
	v_cvt_f32_u32_e32 v42, v40
	v_cvt_f32_u32_e32 v40, v44
	v_subrev_u32_e32 v46, 34, v79
	v_subrev_u32_e32 v47, 35, v79
	v_subrev_u32_e32 v44, 32, v79
	v_subrev_u32_e32 v45, 33, v79
	v_subrev_u32_e32 v49, 49, v79
	v_cvt_f32_i32_e32 v91, v68
	s_movk_i32 s2, 0x41
	v_cvt_f32_u32_e32 v37, v37
	v_cvt_f32_u32_e32 v39, v89
	v_cvt_f32_u32_e32 v38, v88
	v_cvt_f32_u32_e32 v41, v41
	v_cvt_f32_u32_e32 v45, v45
	v_cvt_f32_u32_e32 v44, v44
	v_cvt_f32_u32_e32 v47, v47
	v_cvt_f32_u32_e32 v46, v46
	v_cvt_f32_u32_e32 v49, v49
	v_cmp_gt_u32_e64 s[44:45], s2, v79
	v_cmp_gt_u32_e64 s[48:49], s2, v88
	v_cmp_gt_u32_e64 s[50:51], s2, v89
	s_mov_b32 s2, 0xc2800000
	v_pk_mul_f32 v[74:75], v[70:71], v[72:73] op_sel_hi:[0,1] neg_lo:[0,1] neg_hi:[0,1]
	v_cmp_le_f32_e64 s[54:55], s2, v72
	v_bfe_u32 v72, v152, 2, 2
	v_lshlrev_b32_e32 v76, 3, v152
	v_or_b32_e32 v72, v128, v72
	v_cvt_f32_ubyte0_e32 v36, v79
	s_movk_i32 s46, 0x42
	v_cmp_le_f32_e64 s[52:53], s2, v90
	v_cmp_le_f32_e64 s[56:57], s2, v73
	v_cmp_le_f32_e64 s[58:59], s2, v91
	v_and_b32_e32 v73, 24, v76
	v_mul_u32_u24_e32 v72, 0xa0, v72
	s_lshl_b32 s14, s14, 2
	v_readlane_b32 s2, v255, 44
	v_pk_mul_f32 v[38:39], v[70:71], v[38:39] op_sel_hi:[0,1]
	v_pk_mul_f32 v[36:37], v[70:71], v[36:37] op_sel_hi:[0,1]
	v_pk_mul_f32 v[42:43], v[70:71], v[42:43] op_sel_hi:[0,1]
	v_pk_mul_f32 v[40:41], v[70:71], v[40:41] op_sel_hi:[0,1]
	v_pk_mul_f32 v[46:47], v[70:71], v[46:47] op_sel_hi:[0,1]
	v_pk_mul_f32 v[44:45], v[70:71], v[44:45] op_sel_hi:[0,1]
	v_pk_mul_f32 v[50:51], v[70:71], v[50:51] op_sel_hi:[0,1]
	v_pk_mul_f32 v[48:49], v[70:71], v[48:49] op_sel_hi:[0,1]
	v_pk_mul_f32 v[54:55], v[70:71], v[54:55] op_sel_hi:[0,1]
	v_pk_mul_f32 v[52:53], v[70:71], v[52:53] op_sel_hi:[0,1]
	v_pk_mul_f32 v[58:59], v[70:71], v[58:59] op_sel_hi:[0,1]
	v_pk_mul_f32 v[56:57], v[70:71], v[56:57] op_sel_hi:[0,1]
	v_pk_mul_f32 v[62:63], v[70:71], v[62:63] op_sel_hi:[0,1]
	v_pk_mul_f32 v[60:61], v[70:71], v[60:61] op_sel_hi:[0,1]
	v_pk_mul_f32 v[66:67], v[70:71], v[66:67] op_sel_hi:[0,1]
	v_pk_mul_f32 v[64:65], v[70:71], v[64:65] op_sel_hi:[0,1]
	v_mul_f32_e64 v68, v70, -v90
	v_mul_f32_e64 v71, v70, -v91
	v_mov_b32_e32 v69, v74
	v_mov_b32_e32 v70, v75
	v_cmp_gt_u32_e64 s[46:47], s46, v79
	v_add3_u32 v129, s65, v73, v72
	s_add_u32 s90, s2, s14
	v_readlane_b32 s2, v255, 45
	v_add_u32_e32 v130, v77, v78
	s_waitcnt vmcnt(0)
	v_mov_b64_e32 v[72:73], v[84:85]
	v_mov_b64_e32 v[76:77], v[80:81]
	s_mov_b64 s[12:13], s[76:77]
	s_mov_b64 s[76:77], s[68:69]
	s_mov_b32 s87, 0
	s_mov_b32 s89, s31
	s_addc_u32 s91, s2, 0
	v_mov_b64_e32 v[74:75], v[86:87]
	v_mov_b64_e32 v[78:79], v[82:83]
	ds_write_b128 v123, v[4:7]
	ds_write_b128 v123, v[8:11] offset:40960
	ds_write_b128 v124, v[12:15]
	ds_write_b128 v124, v[16:19] offset:40960
	ds_write_b128 v125, v[20:23]
	ds_write_b128 v125, v[24:27] offset:40960
	ds_write_b128 v126, v[28:31]
	ds_write_b128 v126, v[32:35] offset:40960
	s_waitcnt lgkmcnt(0)
	s_barrier
	s_branch .LBB0_171

; #define LAS __attribute__((address_space(3)))
; __device__ __forceinline__ float fexp2(float x) { return __builtin_amdgcn_exp2f(x); }
; __device__ __forceinline__ f32x4 mfma16(bf16x8 a, bf16x8 b, f32x4 c) { return __builtin_amdgcn_mfma_f32_16x16x32_bf16(a, b, c, 0, 0, 0); }
; __device__ __forceinline__ float xmax16(float x) { auto r = __builtin_amdgcn_permlane16_swap(__float_as_uint(x), __float_as_uint(x), false, false); return fmaxf(__uint_as_float(r[0]), __uint_as_float(r[1])); }
; __device__ __forceinline__ float xmax32(float x) { auto r = __builtin_amdgcn_permlane32_swap(__float_as_uint(x), __float_as_uint(x), false, false); return fmaxf(__uint_as_float(r[0]), __uint_as_float(r[1])); }
; template <int DVT, int NKB> ...
;     ...
;     for (int nb = 0; nb < NKB; ++nb)
; #pragma unroll
;         for (int t = 0; t < 2; ++t) {
;             const LAS unsigned char* kp = kbase + (nb * 32 + t * 16 + fr) * kstr + quad * 16;
;             const bf16x8 k0 = *(const LAS bf16x8*)kp, k1 = *(const LAS bf16x8*)(kp + 64), k2 = *(const LAS bf16x8*)(kp + 128), k3 = *(const LAS bf16x8*)(kp + 192);
;             f32x4 b4;
; #pragma unroll
;             for (int j = 0; j < 4; ++j) b4[j] = nslope * __builtin_fabsf(relq - (float)(nb * 32 + t * 16 + j));
;             f32x4 aa = mfma16(k0, qa0, b4), ab = mfma16(k2, qb0, b4);
;             aa = mfma16(k1, qa1, aa); ab = mfma16(k3, qb1, ab);
; #pragma unroll
;             for (int j = 0; j < 4; ++j) { mxa = fmaxf(mxa, aa[j]); mxb = fmaxf(mxb, ab[j]); }
;             sa[nb][t] = aa; sb[nb][t] = ab;
;         }
;     if (!__any((mxa - ma > -140.f) || (mxb - mb > -140.f))) return;
;     mxa = xmax16(mxa); mxb = xmax16(mxb);
;     mxa = xmax32(mxa); mxb = xmax32(mxb);
;     const float mna = fmaxf(ma, mxa), mnb = fmaxf(mb, mxb);
;     if (__any((mna > ma) || (mnb > mb))) {
;         const float ala = fexp2(ma - mna), alb = fexp2(mb - mnb);
;         la *= ala; lb *= alb;
; #pragma unroll
;         for (int d = 0; d < DVT; ++d) { oa[d] = oa[d] * ala; ob[d] = ob[d] * alb; }
;         ma = mna; mb = mnb;
;     }
.Lpf_skip_da:
	s_or_b64 exec, exec, s[100:101]
	s_mov_b32 s98, 1
	v_or_b32_e32 v84, s55, v139
	v_sub_u32_e32 v84, v138, v84
	v_cvt_f32_i32_e32 v120, v84
	v_add_u32_e32 v3, v158, v3
	v_mov_b32_e32 v137, v136
	ds_read_b128 v[84:87], v3 offset:35840
	ds_read_b128 v[88:91], v3 offset:35904
	v_add_f32_e32 v94, -1.0, v120
	v_pk_add_f32 v[92:93], v[120:121], s[16:17] op_sel_hi:[0,1]
	v_and_b32_e32 v93, 0x7fffffff, v93
	v_and_b32_e32 v92, 0x7fffffff, v92
	v_and_b32_e32 v96, 0x7fffffff, v120
	v_and_b32_e32 v97, 0x7fffffff, v94
	v_pk_mul_f32 v[94:95], v[136:137], v[92:93]
	v_pk_mul_f32 v[92:93], v[0:1], v[96:97]
	ds_read_b128 v[96:99], v3 offset:35968
	ds_read_b128 v[100:103], v3 offset:36032
	s_waitcnt lgkmcnt(1)
	v_mfma_f32_16x16x32_bf16 v[96:99], v[96:99], v[12:15], v[92:95]
	v_add_f32_e64 v122, v120, s26
	v_add_f32_e64 v123, v120, s27
	v_and_b32_e32 v123, 0x7fffffff, v123
	v_and_b32_e32 v122, 0x7fffffff, v122
	v_mfma_f32_16x16x32_bf16 v[84:87], v[84:87], v[16:19], v[92:95]
	v_mul_f32_e64 v122, v136, v122
	v_mul_f32_e64 v123, v137, v123
	s_waitcnt lgkmcnt(0)
	v_mfma_f32_16x16x32_bf16 v[96:99], v[100:103], v[4:7], v[96:99]
	v_add_f32_e64 v100, v120, s18
	v_add_f32_e64 v101, v120, s19
	v_pk_add_f32 v[102:103], v[120:121], s[20:21] op_sel_hi:[0,1]
	v_and_b32_e32 v105, 0x7fffffff, v103
	v_and_b32_e32 v104, 0x7fffffff, v102
	v_and_b32_e32 v101, 0x7fffffff, v101
	v_and_b32_e32 v100, 0x7fffffff, v100
	v_mfma_f32_16x16x32_bf16 v[92:95], v[88:91], v[8:11], v[84:87]
	s_nop 2
	ds_read_b128 v[84:87], v3 offset:40192
	ds_read_b128 v[88:91], v3 offset:40256
	v_pk_mul_f32 v[102:103], v[136:137], v[100:101]
	v_pk_mul_f32 v[100:101], v[0:1], v[104:105]
	ds_read_b128 v[104:107], v3 offset:40320
	ds_read_b128 v[108:111], v3 offset:40384
	s_waitcnt lgkmcnt(1)
	v_mfma_f32_16x16x32_bf16 v[104:107], v[104:107], v[12:15], v[100:103]
	v_mfma_f32_16x16x32_bf16 v[84:87], v[84:87], v[16:19], v[100:103]
	s_waitcnt lgkmcnt(0)
	v_mfma_f32_16x16x32_bf16 v[104:107], v[108:111], v[4:7], v[104:107]
	v_add_f32_e64 v108, v120, s22
	v_add_f32_e64 v109, v120, s23
	v_pk_add_f32 v[110:111], v[120:121], s[24:25] op_sel_hi:[0,1]
	v_and_b32_e32 v113, 0x7fffffff, v111
	v_mfma_f32_16x16x32_bf16 v[100:103], v[88:91], v[8:11], v[84:87]
	s_nop 2
	ds_read_b128 v[84:87], v3 offset:44544
	ds_read_b128 v[88:91], v3 offset:44608
	v_and_b32_e32 v112, 0x7fffffff, v110
	v_and_b32_e32 v109, 0x7fffffff, v109
	v_and_b32_e32 v108, 0x7fffffff, v108
	v_pk_mul_f32 v[110:111], v[136:137], v[108:109]
	v_pk_mul_f32 v[108:109], v[0:1], v[112:113]
	ds_read_b128 v[112:115], v3 offset:44672
	ds_read_b128 v[116:119], v3 offset:44736
	s_waitcnt lgkmcnt(3)
	v_mfma_f32_16x16x32_bf16 v[84:87], v[84:87], v[16:19], v[108:111]
	v_pk_add_f32 v[120:121], v[120:121], s[28:29] op_sel_hi:[0,1]
	v_and_b32_e32 v121, 0x7fffffff, v121
	v_and_b32_e32 v120, 0x7fffffff, v120
	s_waitcnt lgkmcnt(1)
	v_mfma_f32_16x16x32_bf16 v[108:111], v[112:115], v[12:15], v[108:111]
	v_max3_f32 v112, v92, s96, v93
	v_max3_f32 v124, v112, v94, v95
	v_pk_mul_f32 v[120:121], v[0:1], v[120:121]
	v_mfma_f32_16x16x32_bf16 v[84:87], v[88:91], v[8:11], v[84:87]
	v_max3_f32 v88, v96, s96, v97
	v_max3_f32 v125, v88, v98, v99
	v_max3_f32 v0, v124, v100, v101
	s_waitcnt lgkmcnt(0)
	v_mfma_f32_16x16x32_bf16 v[88:91], v[116:119], v[4:7], v[108:111]
	s_nop 2
	ds_read_b128 v[108:111], v3 offset:48896
	ds_read_b128 v[112:115], v3 offset:48960
	ds_read_b128 v[116:119], v3 offset:49024
	v_max3_f32 v1, v125, v104, v105
	v_max3_f32 v0, v0, v102, v103
	s_waitcnt lgkmcnt(2)
	v_mfma_f32_16x16x32_bf16 v[16:19], v[108:111], v[16:19], v[120:123]
	ds_read_b128 v[108:111], v3 offset:49088
	v_max3_f32 v1, v1, v106, v107
	v_max3_f32 v0, v0, v84, v85
	s_waitcnt lgkmcnt(1)
	v_mfma_f32_16x16x32_bf16 v[12:15], v[116:119], v[12:15], v[120:123]
	v_max3_f32 v1, v1, v88, v89
	v_max3_f32 v0, v0, v86, v87
	v_max3_f32 v1, v1, v90, v91
	v_mfma_f32_16x16x32_bf16 v[8:11], v[112:115], v[8:11], v[16:19]
	s_waitcnt lgkmcnt(0)
	v_mfma_f32_16x16x32_bf16 v[4:7], v[108:111], v[4:7], v[12:15]
	s_nop 5
	v_max3_f32 v0, v0, v8, v9
	s_nop 0
	v_max3_f32 v3, v1, v4, v5
	v_max3_f32 v1, v0, v10, v11
	v_max3_f32 v0, v3, v6, v7
	v_sub_f32_e32 v3, v1, v159
	v_sub_f32_e32 v12, v0, v154
	v_max_f32_e32 v3, v3, v12
	v_cmp_lt_f32_e32 vcc, s37, v3
	s_cbranch_vccz .LBB0_222
	v_mov_b32_e32 v3, v1
	s_nop 1
	v_permlane16_swap_b32_e32 v1, v3
	v_max_f32_e32 v3, v3, v3
	v_max_f32_e32 v1, v1, v1
	v_max_f32_e32 v1, v1, v3
	v_mov_b32_e32 v3, v0
	s_nop 1
	v_permlane16_swap_b32_e32 v0, v3
	v_max_f32_e32 v3, v3, v3
	v_max_f32_e32 v0, v0, v0
	v_max_f32_e32 v0, v0, v3
	v_mov_b32_e32 v3, v1
	v_mov_b32_e32 v12, v0
	s_nop 0
	v_permlane32_swap_b32_e32 v1, v3
	v_permlane32_swap_b32_e32 v0, v12
	v_max3_f32 v3, v159, v1, v3
	v_max3_f32 v0, v154, v0, v12
	v_cmp_gt_f32_e32 vcc, v3, v159
	v_cmp_gt_f32_e64 s[42:43], v0, v154
	s_or_b64 vcc, vcc, s[42:43]
	s_cbranch_vccz .LBB0_220
	v_sub_f32_e32 v1, v159, v3
	v_exp_f32_e32 v12, v1
	v_sub_f32_e32 v1, v154, v0
	v_exp_f32_e32 v13, v1
	v_mov_b32_e32 v154, v0
	v_mov_b32_e32 v14, v13
	v_pk_mul_f32 v[134:135], v[134:135], v[12:13]
	v_pk_mul_f32 v[70:71], v[70:71], v[14:15] op_sel_hi:[1,0]
	v_pk_mul_f32 v[68:69], v[68:69], v[14:15] op_sel_hi:[1,0]
	v_pk_mul_f32 v[66:67], v[66:67], v[14:15] op_sel_hi:[1,0]
	v_pk_mul_f32 v[64:65], v[64:65], v[14:15] op_sel_hi:[1,0]
	v_pk_mul_f32 v[50:51], v[50:51], v[14:15] op_sel_hi:[1,0]
	v_pk_mul_f32 v[48:49], v[48:49], v[14:15] op_sel_hi:[1,0]
	v_pk_mul_f32 v[62:63], v[62:63], v[14:15] op_sel_hi:[1,0]
	v_pk_mul_f32 v[60:61], v[60:61], v[14:15] op_sel_hi:[1,0]
	v_pk_mul_f32 v[54:55], v[54:55], v[14:15] op_sel_hi:[1,0]
	v_pk_mul_f32 v[52:53], v[52:53], v[14:15] op_sel_hi:[1,0]
	v_pk_mul_f32 v[58:59], v[58:59], v[14:15] op_sel_hi:[1,0]
	v_pk_mul_f32 v[56:57], v[56:57], v[14:15] op_sel_hi:[1,0]
	v_pk_mul_f32 v[82:83], v[82:83], v[14:15] op_sel_hi:[1,0]
	v_pk_mul_f32 v[80:81], v[80:81], v[14:15] op_sel_hi:[1,0]
	v_pk_mul_f32 v[74:75], v[74:75], v[12:13] op_sel_hi:[1,0]
	v_pk_mul_f32 v[72:73], v[72:73], v[12:13] op_sel_hi:[1,0]
	v_pk_mul_f32 v[46:47], v[46:47], v[12:13] op_sel_hi:[1,0]
	v_pk_mul_f32 v[44:45], v[44:45], v[12:13] op_sel_hi:[1,0]
	v_pk_mul_f32 v[26:27], v[26:27], v[12:13] op_sel_hi:[1,0]
	v_pk_mul_f32 v[24:25], v[24:25], v[12:13] op_sel_hi:[1,0]
	v_pk_mul_f32 v[30:31], v[30:31], v[12:13] op_sel_hi:[1,0]
	v_pk_mul_f32 v[28:29], v[28:29], v[12:13] op_sel_hi:[1,0]
	v_pk_mul_f32 v[42:43], v[42:43], v[12:13] op_sel_hi:[1,0]
	v_pk_mul_f32 v[40:41], v[40:41], v[12:13] op_sel_hi:[1,0]
	v_pk_mul_f32 v[22:23], v[22:23], v[12:13] op_sel_hi:[1,0]
	v_pk_mul_f32 v[20:21], v[20:21], v[12:13] op_sel_hi:[1,0]
	v_pk_mul_f32 v[34:35], v[34:35], v[12:13] op_sel_hi:[1,0]
	v_pk_mul_f32 v[32:33], v[32:33], v[12:13] op_sel_hi:[1,0]
	v_pk_mul_f32 v[38:39], v[38:39], v[12:13] op_sel_hi:[1,0]
	v_pk_mul_f32 v[36:37], v[36:37], v[12:13] op_sel_hi:[1,0]
	v_pk_mul_f32 v[78:79], v[78:79], v[14:15] op_sel_hi:[1,0]
	v_pk_mul_f32 v[76:77], v[76:77], v[14:15] op_sel_hi:[1,0]
	s_branch .LBB0_221
